# grid barrier: last workgroup of an XCD adds to the top counter without waiting for the old value and all workgroups watch the top counter (one round trip less per seam); on top of p1loop+p1nt+tailnt+g
# baseline (speedup 1.0000x reference)
.LBB0_42:
	v_readlane_b32 s2, v253, 2
	s_lshl_b32 s2, s2, 8
	s_add_u32 s2, s70, s2
	s_addc_u32 s3, s71, 0
	v_mov_b32_e32 v2, 0x1000
	v_mov_b32_e32 v4, 1
	global_atomic_add v4, v2, v4, s[2:3] offset:1024 sc0
	s_waitcnt vmcnt(0) lgkmcnt(0)
	v_readfirstlane_b32 s2, v4
	v_readfirstlane_b32 s3, v3
	v_readfirstlane_b32 s8, v1
	s_mov_b32 s9, 0
	s_nop 1
.Lsb0_q:
	s_cmp_ge_u32 s2, s3
	s_cbranch_scc0 .Lsb0_qd
	s_sub_u32 s2, s2, s3
	s_add_u32 s9, s9, 1
	s_branch .Lsb0_q
.Lsb0_qd:
	s_add_u32 s2, s2, 1
	s_add_u32 s9, s9, 1
	s_mul_i32 s9, s9, s8
	v_mov_b32_e32 v2, 0x4000
	s_cmp_eq_u32 s2, s3
	s_cbranch_scc0 .Lsb0_poll
	buffer_wbl2 sc1
	s_waitcnt vmcnt(0)
	v_mov_b32_e32 v4, 1
	global_atomic_add v2, v4, s[44:45] offset:1024
.Lsb0_poll:
	s_mov_b32 s8, 0
.Lsb0_pl:
	global_load_dword v3, v2, s[44:45] offset:1024 sc1
	s_waitcnt vmcnt(0)
	v_readfirstlane_b32 s2, v3
	s_nop 1
	s_cmp_ge_u32 s2, s9
	s_cbranch_scc1 .Lsb0_pd
	s_add_u32 s8, s8, 1
	s_cmp_lt_u32 s8, 0x4000
	s_cbranch_scc0 .Lsb0_pd
	s_sleep 1
	s_branch .Lsb0_pl
.Lsb0_pd:
	buffer_inv sc1
	s_waitcnt vmcnt(0)

.LBB0_129:
	v_readlane_b32 s2, v253, 2
	s_lshl_b32 s2, s2, 8
	v_readlane_b32 s6, v253, 21
	v_readlane_b32 s7, v253, 22
	s_add_u32 s2, s6, s2
	s_addc_u32 s3, s7, 0
	v_mov_b32_e32 v2, 0x1000
	v_mov_b32_e32 v4, 1
	global_atomic_add v4, v2, v4, s[2:3] offset:1024 sc0
	s_waitcnt vmcnt(0) lgkmcnt(0)
	v_readfirstlane_b32 s2, v4
	v_readfirstlane_b32 s3, v3
	v_readfirstlane_b32 s8, v1
	s_mov_b32 s9, 0
	s_nop 1

.LBB0_723:
	v_readlane_b32 s2, v253, 2
	s_lshl_b32 s2, s2, 8
	s_add_u32 s2, s80, s2
	s_addc_u32 s3, s81, 0
	v_mov_b32_e32 v2, 0x1000
	v_mov_b32_e32 v4, 1
	global_atomic_add v4, v2, v4, s[2:3] offset:1024 sc0
	s_waitcnt vmcnt(0) lgkmcnt(0)
	v_readfirstlane_b32 s2, v4
	v_readfirstlane_b32 s3, v3
	v_readfirstlane_b32 s8, v1
	s_mov_b32 s9, 0
	s_nop 1
